# rowB xf stores marked nt (xf is only re-read two phases later; keep XN and weights resident instead)
# speedup vs baseline: 1.0093x; 1.0026x over previous
; #define GAS __attribute__((address_space(1)))
; __device__ __forceinline__ float wave_sum(float v) { v = red16(v); return (rdlane(v, 0) + rdlane(v, 16)) + (rdlane(v, 32) + rdlane(v, 48)); }
; __device__ __forceinline__ void rowB_phase(ArgP A, int layer, int lane, int wave, int bid, int G) {
;     ...
;         float s = 0.f;
; #pragma unroll
;         for (int j = 0; j < 8; ++j) s += (mv[j].x * mv[j].x + mv[j].y * mv[j].y) + (mv[j].z * mv[j].z + mv[j].w * mv[j].w);
;         const float r1 = rsqrtf(wave_sum(s) * (1.0f / DM) + 1e-6f); float s2 = 0.f;
; #pragma unroll
;         for (int j = 0; j < 8; ++j) { const f32x4 g = ((const GAS f32x4*)gpost)[64 * j + lane]; xv[j] = xv[j] + mv[j] * r1 * g; s2 += (xv[j].x * xv[j].x + xv[j].y * xv[j].y) + (xv[j].z * xv[j].z + xv[j].w * xv[j].w); }
.LBB0_1544:
	s_waitcnt vmcnt(0)
	v_pk_mul_f32 v[168:169], v[128:129], v[128:129]
	v_pk_mul_f32 v[170:171], v[124:125], v[124:125]
	v_pk_mul_f32 v[172:173], v[122:123], v[122:123]
	v_pk_mul_f32 v[174:175], v[126:127], v[126:127]
	v_pk_mul_f32 v[164:165], v[112:113], v[112:113]
	v_pk_mul_f32 v[166:167], v[110:111], v[110:111]
	v_mov_b32_e32 v176, v174
	v_mov_b32_e32 v177, v172
	v_mov_b32_e32 v172, v175
	v_mov_b32_e32 v174, v168
	v_mov_b32_e32 v175, v170
	v_mov_b32_e32 v170, v169
	v_pk_add_f32 v[168:169], v[174:175], v[170:171]
	v_pk_mov_b32 v[170:171], v[166:167], v[164:165] op_sel:[1,0]
	v_mov_b32_e32 v167, v165
	v_pk_add_f32 v[164:165], v[170:171], v[166:167]
	v_pk_add_f32 v[172:173], v[176:177], v[172:173]
	v_pk_add_f32 v[164:165], v[164:165], v[164:165] op_sel_hi:[0,1]
	v_mul_f32_e32 v164, v102, v102
	v_pk_add_f32 v[168:169], v[172:173], v[168:169]
	v_pk_fma_f32 v[166:167], v[102:103], v[102:103], v[164:165] op_sel_hi:[1,1,0]
	v_mul_f32_e32 v164, v104, v104
	v_pk_add_f32 v[168:169], v[168:169], v[168:169] op_sel_hi:[0,1]
	v_pk_fma_f32 v[170:171], v[104:105], v[104:105], v[164:165] op_sel_hi:[1,1,0]
	v_mul_f32_e32 v166, v98, v98
	v_mul_f32_e32 v170, v99, v99
	v_mul_f32_e32 v164, v100, v100
	v_mul_f32_e32 v168, v101, v101
	v_pk_mul_f32 v[158:159], v[88:89], v[88:89]
	v_pk_mul_f32 v[162:163], v[86:87], v[86:87]
	v_pk_add_f32 v[166:167], v[166:167], v[170:171]
	v_pk_add_f32 v[164:165], v[164:165], v[168:169]
	s_mov_b32 s19, s83
	v_pk_add_f32 v[164:165], v[166:167], v[164:165]
	v_pk_mov_b32 v[166:167], v[162:163], v[158:159] op_sel:[1,0]
	v_mov_b32_e32 v163, v159
	v_pk_add_f32 v[158:159], v[166:167], v[162:163]
	v_pk_add_f32 v[164:165], v[164:165], v[164:165] op_sel_hi:[0,1]
	v_pk_add_f32 v[158:159], v[158:159], v[158:159] op_sel_hi:[0,1]
	v_mul_f32_e32 v158, v82, v82
	v_pk_fma_f32 v[162:163], v[82:83], v[82:83], v[158:159] op_sel_hi:[1,1,0]
	v_mul_f32_e32 v158, v84, v84
	v_pk_fma_f32 v[166:167], v[84:85], v[84:85], v[158:159] op_sel_hi:[1,1,0]
	v_mul_f32_e32 v162, v74, v74
	v_mul_f32_e32 v166, v75, v75
	v_mul_f32_e32 v158, v76, v76
	v_mul_f32_e32 v164, v77, v77
	v_pk_add_f32 v[162:163], v[162:163], v[166:167]
	v_pk_add_f32 v[158:159], v[158:159], v[164:165]
	s_nop 0
	v_pk_add_f32 v[158:159], v[162:163], v[158:159]
	global_load_dwordx4 v[162:165], v[130:131], off
	v_add_f32_e32 v133, v158, v159
	s_nop 1
	v_add_f32_dpp v133, v133, v133 quad_perm:[1,0,3,2] row_mask:0xf bank_mask:0xf bound_ctrl:1
	s_nop 1
	v_add_f32_dpp v133, v133, v133 quad_perm:[2,3,0,1] row_mask:0xf bank_mask:0xf bound_ctrl:1
	s_nop 1
	v_add_f32_dpp v133, v133, v133 row_half_mirror row_mask:0xf bank_mask:0xf bound_ctrl:1
	s_nop 1
	v_add_f32_dpp v133, v133, v133 row_mirror row_mask:0xf bank_mask:0xf bound_ctrl:1
	s_nop 0
	v_readlane_b32 s2, v133, 16
	v_readlane_b32 s3, v133, 48
	v_readlane_b32 s0, v133, 0
	v_readlane_b32 s1, v133, 32
	v_mov_b32_e32 v158, s2
	v_mov_b32_e32 v159, s3
	v_pk_add_f32 v[158:159], s[0:1], v[158:159]
	s_nop 0
	v_add_f32_e32 v133, v158, v159
	v_fmamk_f32 v133, v133, 0x3a000000, v197
	v_cmp_gt_f32_e32 vcc, s96, v133
	v_mul_f32_e32 v137, 0x4b800000, v133
	s_nop 0
	v_cndmask_b32_e32 v133, v133, v137, vcc
	v_rsq_f32_e32 v133, v133
	s_nop 0
	v_mul_f32_e32 v137, 0x45800000, v133
	v_cndmask_b32_e32 v158, v133, v137, vcc
	v_pk_mul_f32 v[126:127], v[126:127], v[158:159] op_sel_hi:[1,0]
	v_pk_mul_f32 v[128:129], v[128:129], v[158:159] op_sel_hi:[1,0]
	v_pk_mul_f32 v[122:123], v[122:123], v[158:159] op_sel_hi:[1,0]
	v_pk_mul_f32 v[124:125], v[124:125], v[158:159] op_sel_hi:[1,0]
	v_pk_mul_f32 v[110:111], v[110:111], v[158:159] op_sel_hi:[1,0]
	v_pk_mul_f32 v[112:113], v[112:113], v[158:159] op_sel_hi:[1,0]
	v_pk_mul_f32 v[102:103], v[102:103], v[158:159] op_sel_hi:[1,0]
	v_pk_mul_f32 v[104:105], v[104:105], v[158:159] op_sel_hi:[1,0]
	v_pk_mul_f32 v[98:99], v[98:99], v[158:159] op_sel_hi:[1,0]
	v_pk_mul_f32 v[100:101], v[100:101], v[158:159] op_sel_hi:[1,0]
	v_pk_mul_f32 v[86:87], v[86:87], v[158:159] op_sel_hi:[1,0]
	v_pk_mul_f32 v[88:89], v[88:89], v[158:159] op_sel_hi:[1,0]
	v_pk_mul_f32 v[82:83], v[82:83], v[158:159] op_sel_hi:[1,0]
	v_pk_mul_f32 v[84:85], v[84:85], v[158:159] op_sel_hi:[1,0]
	v_pk_mul_f32 v[74:75], v[74:75], v[158:159] op_sel_hi:[1,0]
	v_pk_mul_f32 v[76:77], v[76:77], v[158:159] op_sel_hi:[1,0]
	s_waitcnt vmcnt(0)
	v_pk_fma_f32 v[120:121], v[164:165], v[128:129], v[120:121]
	v_pk_fma_f32 v[118:119], v[162:163], v[126:127], v[118:119]
	global_load_dwordx4 v[126:129], v[130:131], off offset:1024
	s_waitcnt vmcnt(0)
	v_pk_fma_f32 v[114:115], v[126:127], v[122:123], v[114:115]
	v_pk_fma_f32 v[116:117], v[128:129], v[124:125], v[116:117]
	v_mov_b32_e32 v124, v119
	v_mov_b32_e32 v125, v115
	v_mov_b32_e32 v122, v118
	v_mov_b32_e32 v123, v114
	v_pk_mul_f32 v[124:125], v[124:125], v[124:125]
	v_mov_b32_e32 v126, v121
	v_mov_b32_e32 v127, v117
	v_pk_fma_f32 v[122:123], v[122:123], v[122:123], v[124:125]
	v_mov_b32_e32 v124, v120
	v_mov_b32_e32 v125, v116
	v_pk_mul_f32 v[126:127], v[126:127], v[126:127]
	v_mov_b32_e32 v128, v32
	v_pk_fma_f32 v[124:125], v[124:125], v[124:125], v[126:127]
	v_mov_b32_e32 v129, v33
	v_pk_add_f32 v[122:123], v[122:123], v[124:125]
	global_load_dwordx4 v[124:127], v[130:131], off offset:2048
	v_pk_add_f32 v[122:123], v[122:123], v[122:123] op_sel_hi:[0,1]
	s_waitcnt vmcnt(0)
	v_pk_fma_f32 v[108:109], v[126:127], v[112:113], v[108:109]
	v_pk_fma_f32 v[106:107], v[124:125], v[110:111], v[106:107]
	v_pk_mul_f32 v[110:111], v[108:109], v[108:109]
	v_pk_mul_f32 v[112:113], v[106:107], v[106:107]
	v_mov_b32_e32 v126, v30
	v_pk_mov_b32 v[124:125], v[112:113], v[110:111] op_sel:[1,0]
	v_mov_b32_e32 v113, v111
	v_pk_add_f32 v[110:111], v[124:125], v[112:113]
	v_mov_b32_e32 v127, v31
	v_pk_add_f32 v[124:125], v[110:111], v[110:111] op_sel_hi:[0,1]
	global_load_dwordx4 v[110:113], v[130:131], off offset:3072
	s_waitcnt vmcnt(0)
; #define GAS __attribute__((address_space(1)))
; __device__ __forceinline__ unsigned pk2(float lo, float hi) { return pg8::cvt_pk_bf16(lo, hi); }
; __device__ __forceinline__ float wave_sum(float v) { v = red16(v); return (rdlane(v, 0) + rdlane(v, 16)) + (rdlane(v, 32) + rdlane(v, 48)); }
; __device__ __forceinline__ void rowB_phase(ArgP A, int layer, int lane, int wave, int bid, int G) {
;     ...
;         const float r1 = rsqrtf(wave_sum(s) * (1.0f / DM) + 1e-6f); float s2 = 0.f;
; #pragma unroll
;         for (int j = 0; j < 8; ++j) { const f32x4 g = ((const GAS f32x4*)gpost)[64 * j + lane]; xv[j] = xv[j] + mv[j] * r1 * g; s2 += (xv[j].x * xv[j].x + xv[j].y * xv[j].y) + (xv[j].z * xv[j].z + xv[j].w * xv[j].w); }
;         const float r2 = rsqrtf(wave_sum(s2) * (1.0f / DM) + 1e-6f);
;         GAS f32x4* xf = (GAS f32x4*)(A->ws + WS_XF) + (size_t)m * (DM / 4); GAS u32x2* xn = (GAS u32x2*)(A->ws + WS_XN) + (size_t)m * (DM / 4);
; #pragma unroll
;         for (int j = 0; j < 8; ++j) { const f32x4 g = ((const GAS f32x4*)gpre)[64 * j + lane]; xf[64 * j + lane] = xv[j];
;             u32x2 w; w.x = pk2(xv[j].x * r2 * g.x, xv[j].y * r2 * g.y); w.y = pk2(xv[j].z * r2 * g.z, xv[j].w * r2 * g.w); xn[64 * j + lane] = w; }
	v_pk_fma_f32 v[94:95], v[110:111], v[102:103], v[94:95]
	v_pk_fma_f32 v[96:97], v[112:113], v[104:105], v[96:97]
	v_mul_f32_e32 v102, v94, v94
	v_pk_fma_f32 v[110:111], v[94:95], v[94:95], v[102:103] op_sel_hi:[1,1,0]
	v_mul_f32_e32 v102, v96, v96
	v_pk_fma_f32 v[112:113], v[96:97], v[96:97], v[102:103] op_sel_hi:[1,1,0]
	global_load_dwordx4 v[102:105], v[134:135], off
	s_waitcnt vmcnt(0)
	v_pk_fma_f32 v[92:93], v[104:105], v[100:101], v[92:93]
	v_pk_fma_f32 v[90:91], v[102:103], v[98:99], v[90:91]
	v_mul_f32_e32 v124, v92, v92
	v_mul_f32_e32 v110, v90, v90
	v_mul_f32_e32 v112, v91, v91
	v_mul_f32_e32 v122, v93, v93
	v_pk_add_f32 v[98:99], v[110:111], v[112:113]
	v_pk_add_f32 v[100:101], v[124:125], v[122:123]
	v_mov_b32_e32 v122, v26
	v_pk_add_f32 v[98:99], v[98:99], v[100:101]
	global_load_dwordx4 v[100:103], v[138:139], off
	v_pk_add_f32 v[98:99], v[98:99], v[98:99] op_sel_hi:[0,1]
	v_mov_b32_e32 v123, v27
	v_mov_b32_e32 v124, v28
	v_mov_b32_e32 v125, v29
	v_mov_b32_e32 v110, v22
	v_mov_b32_e32 v111, v23
	v_mov_b32_e32 v112, v24
	v_mov_b32_e32 v113, v25
	v_mov_b32_e32 v104, v20
	v_mov_b32_e32 v105, v21
	s_waitcnt vmcnt(0)
	v_pk_fma_f32 v[80:81], v[102:103], v[88:89], v[80:81]
	v_pk_fma_f32 v[78:79], v[100:101], v[86:87], v[78:79]
	v_pk_mul_f32 v[86:87], v[80:81], v[80:81]
	v_pk_mul_f32 v[88:89], v[78:79], v[78:79]
	v_mov_b32_e32 v102, v18
	v_pk_mov_b32 v[100:101], v[88:89], v[86:87] op_sel:[1,0]
	v_mov_b32_e32 v89, v87
	v_pk_add_f32 v[86:87], v[100:101], v[88:89]
	v_mov_b32_e32 v103, v19
	v_pk_add_f32 v[100:101], v[86:87], v[86:87] op_sel_hi:[0,1]
	global_load_dwordx4 v[86:89], v[142:143], off
	s_waitcnt vmcnt(0)
	v_pk_fma_f32 v[70:71], v[86:87], v[82:83], v[70:71]
	v_pk_fma_f32 v[72:73], v[88:89], v[84:85], v[72:73]
	v_mul_f32_e32 v82, v70, v70
	v_pk_fma_f32 v[86:87], v[70:71], v[70:71], v[82:83] op_sel_hi:[1,1,0]
	v_mul_f32_e32 v82, v72, v72
	v_pk_fma_f32 v[88:89], v[72:73], v[72:73], v[82:83] op_sel_hi:[1,1,0]
	global_load_dwordx4 v[82:85], v[146:147], off
	s_waitcnt vmcnt(0)
	v_pk_fma_f32 v[68:69], v[84:85], v[76:77], v[68:69]
	v_pk_fma_f32 v[66:67], v[82:83], v[74:75], v[66:67]
	v_mul_f32_e32 v100, v68, v68
	v_mul_f32_e32 v86, v66, v66
	v_mul_f32_e32 v88, v67, v67
	v_mul_f32_e32 v98, v69, v69
	v_pk_add_f32 v[74:75], v[86:87], v[88:89]
	v_pk_add_f32 v[76:77], v[100:101], v[98:99]
	v_mov_b32_e32 v98, v12
	v_pk_add_f32 v[74:75], v[74:75], v[76:77]
	v_mov_b32_e32 v99, v13
	v_add_f32_e32 v74, v74, v75
	v_mov_b32_e32 v100, v14
	v_mov_b32_e32 v101, v15
	v_add_f32_dpp v74, v74, v74 quad_perm:[1,0,3,2] row_mask:0xf bank_mask:0xf bound_ctrl:1
	v_mov_b32_e32 v88, v10
	v_mov_b32_e32 v89, v11
	v_add_f32_dpp v74, v74, v74 quad_perm:[2,3,0,1] row_mask:0xf bank_mask:0xf bound_ctrl:1
	s_nop 1
	v_add_f32_dpp v74, v74, v74 row_half_mirror row_mask:0xf bank_mask:0xf bound_ctrl:1
	s_nop 1
	v_add_f32_dpp v74, v74, v74 row_mirror row_mask:0xf bank_mask:0xf bound_ctrl:1
	s_nop 0
	v_readlane_b32 s2, v74, 16
	v_readlane_b32 s3, v74, 48
	v_readlane_b32 s0, v74, 0
	v_readlane_b32 s1, v74, 32
	v_mov_b32_e32 v74, s2
	v_mov_b32_e32 v75, s3
	v_pk_add_f32 v[74:75], s[0:1], v[74:75]
	s_load_dwordx2 s[0:1], s[12:13], 0x138
	v_add_f32_e32 v74, v74, v75
	v_fmamk_f32 v74, v74, 0x3a000000, v197
	v_cmp_gt_f32_e32 vcc, s96, v74
	v_mul_f32_e32 v75, 0x4b800000, v74
	s_lshl_b64 s[2:3], s[18:19], 13
	v_cndmask_b32_e32 v74, v74, v75, vcc
	v_rsq_f32_e32 v74, v74
	s_waitcnt lgkmcnt(0)
	s_add_u32 s2, s0, s2
	s_addc_u32 s3, s1, s3
	s_add_u32 s4, s2, 0x1f100000
	v_mul_f32_e32 v75, 0x45800000, v74
	v_cndmask_b32_e32 v82, v74, v75, vcc
	global_load_dwordx4 v[74:77], v[148:149], off
	v_mul_f32_e32 v83, v118, v82
	s_addc_u32 s5, s3, 0
	s_lshl_b64 s[2:3], s[18:19], 12
	global_store_dwordx4 v16, v[118:121], s[4:5] nt
	s_add_u32 s18, s0, s2
	s_addc_u32 s19, s1, s3
	s_mov_b64 s[0:1], 0xd880000
	s_mov_b32 s2, s15
	s_waitcnt vmcnt(1)
	v_mul_f32_e32 v74, v74, v83
	v_mul_f32_e32 v83, v119, v82
	v_mul_f32_e32 v75, v75, v83
	v_cvt_pk_bf16_f32 v84, v74, v75
	v_mul_f32_e32 v74, v120, v82
	v_mul_f32_e32 v75, v121, v82
	v_mul_f32_e32 v74, v76, v74
	v_mul_f32_e32 v75, v77, v75
	v_cvt_pk_bf16_f32 v85, v74, v75
	v_lshlrev_b32_e32 v74, 3, v160
	v_mov_b32_e32 v75, v17
	v_lshl_add_u64 v[76:77], s[18:19], 0, v[74:75]
	v_lshl_add_u64 v[74:75], v[76:77], 0, s[0:1]
	s_mov_b32 s0, 0xd880000
	v_add_co_u32_e32 v76, vcc, s0, v76
	v_mul_f32_e32 v83, v117, v82
	s_nop 0
	v_addc_co_u32_e32 v77, vcc, 0, v77, vcc
	global_store_dwordx2 v[76:77], v[84:85], off
	global_load_dwordx4 v[84:87], v[148:149], off offset:1024
	v_mul_f32_e32 v76, v114, v82
	v_mul_f32_e32 v77, v115, v82
	global_store_dwordx4 v16, v[114:117], s[4:5] offset:1024 nt
	v_mov_b64_e32 v[120:121], v[36:37]
	s_andn2_b64 vcc, exec, s[16:17]
	v_mov_b64_e32 v[118:119], v[34:35]
	s_mov_b32 s18, s6
	s_waitcnt vmcnt(1)
; #define GAS __attribute__((address_space(1)))
; __device__ __forceinline__ unsigned pk2(float lo, float hi) { return pg8::cvt_pk_bf16(lo, hi); }
; __device__ __forceinline__ void rowB_phase(ArgP A, int layer, int lane, int wave, int bid, int G) {
;     ...
;         GAS f32x4* xf = (GAS f32x4*)(A->ws + WS_XF) + (size_t)m * (DM / 4); GAS u32x2* xn = (GAS u32x2*)(A->ws + WS_XN) + (size_t)m * (DM / 4);
; #pragma unroll
;         for (int j = 0; j < 8; ++j) { const f32x4 g = ((const GAS f32x4*)gpre)[64 * j + lane]; xf[64 * j + lane] = xv[j];
;             u32x2 w; w.x = pk2(xv[j].x * r2 * g.x, xv[j].y * r2 * g.y); w.y = pk2(xv[j].z * r2 * g.z, xv[j].w * r2 * g.w); xn[64 * j + lane] = w; }
; #pragma unroll
;         for (int j = 0; j < 8; ++j) { xv[j] = xn2[j]; mv[j] = mn2[j]; }
;         m = mn;
	v_mul_f32_e32 v76, v84, v76
	v_mul_f32_e32 v77, v85, v77
	v_cvt_pk_bf16_f32 v76, v76, v77
	v_mul_f32_e32 v77, v116, v82
	v_mul_f32_e32 v77, v86, v77
	v_mul_f32_e32 v83, v87, v83
	v_cvt_pk_bf16_f32 v77, v77, v83
	global_store_dwordx2 v[74:75], v[76:77], off offset:512
	global_load_dwordx4 v[84:87], v[148:149], off offset:2048
	v_mul_f32_e32 v76, v106, v82
	v_mul_f32_e32 v77, v107, v82
	global_store_dwordx4 v16, v[106:109], s[4:5] offset:2048 nt
	v_mul_f32_e32 v83, v109, v82
	v_mov_b64_e32 v[116:117], v[40:41]
	v_mov_b64_e32 v[114:115], v[38:39]
	s_waitcnt vmcnt(1)
	v_mul_f32_e32 v76, v76, v84
	v_mul_f32_e32 v77, v77, v85
	v_cvt_pk_bf16_f32 v76, v76, v77
	v_mul_f32_e32 v77, v108, v82
	v_mul_f32_e32 v77, v77, v86
	v_mul_f32_e32 v83, v83, v87
	v_cvt_pk_bf16_f32 v77, v77, v83
	global_store_dwordx2 v[74:75], v[76:77], off offset:1024
	global_load_dwordx4 v[84:87], v[148:149], off offset:3072
	v_mul_f32_e32 v76, v94, v82
	v_mul_f32_e32 v77, v95, v82
	global_store_dwordx4 v16, v[94:97], s[4:5] offset:3072 nt
	v_mul_f32_e32 v83, v97, v82
	v_mov_b64_e32 v[108:109], v[44:45]
	v_mov_b64_e32 v[106:107], v[42:43]
	s_waitcnt vmcnt(1)
	v_mul_f32_e32 v76, v76, v84
	v_mul_f32_e32 v77, v77, v85
	v_cvt_pk_bf16_f32 v76, v76, v77
	v_mul_f32_e32 v77, v96, v82
	v_mul_f32_e32 v77, v77, v86
	v_mul_f32_e32 v83, v83, v87
	v_cvt_pk_bf16_f32 v77, v77, v83
	global_store_dwordx2 v[74:75], v[76:77], off offset:1536
	global_load_dwordx4 v[84:87], v[150:151], off
	v_mul_f32_e32 v76, v90, v82
	v_mul_f32_e32 v77, v91, v82
	global_store_dwordx4 v132, v[90:93], s[4:5] nt
	v_mul_f32_e32 v83, v93, v82
	v_mov_b64_e32 v[96:97], v[48:49]
	v_mov_b64_e32 v[94:95], v[46:47]
	s_waitcnt vmcnt(1)
	v_mul_f32_e32 v76, v76, v84
	v_mul_f32_e32 v77, v77, v85
	v_cvt_pk_bf16_f32 v76, v76, v77
	v_mul_f32_e32 v77, v92, v82
	v_mul_f32_e32 v77, v77, v86
	v_mul_f32_e32 v83, v83, v87
	v_cvt_pk_bf16_f32 v77, v77, v83
	global_store_dwordx2 v[74:75], v[76:77], off offset:2048
	global_load_dwordx4 v[84:87], v[152:153], off
	v_mul_f32_e32 v76, v78, v82
	v_mul_f32_e32 v77, v79, v82
	global_store_dwordx4 v136, v[78:81], s[4:5] nt
	v_mov_b64_e32 v[92:93], v[52:53]
	v_mov_b64_e32 v[90:91], v[50:51]
	v_mul_f32_e32 v78, v81, v82
	v_mov_b32_e32 v83, v5
	s_waitcnt vmcnt(1)
	v_mul_f32_e32 v76, v76, v84
	v_mul_f32_e32 v77, v77, v85
	v_cvt_pk_bf16_f32 v76, v76, v77
	v_mul_f32_e32 v77, v80, v82
	v_mul_f32_e32 v77, v77, v86
	v_mul_f32_e32 v78, v78, v87
	v_cvt_pk_bf16_f32 v77, v77, v78
	global_store_dwordx2 v[74:75], v[76:77], off offset:2560
	global_load_dwordx4 v[76:79], v[154:155], off
	v_mov_b32_e32 v86, v8
	global_store_dwordx4 v140, v[70:73], s[4:5] nt
	v_mov_b32_e32 v87, v9
	v_mov_b32_e32 v84, v6
	v_mul_f32_e32 v70, v70, v82
	v_mul_f32_e32 v71, v71, v82
	v_mov_b32_e32 v85, v7
	s_waitcnt vmcnt(1)
	v_mul_f32_e32 v70, v70, v76
	v_mul_f32_e32 v71, v71, v77
	v_cvt_pk_bf16_f32 v70, v70, v71
	v_mul_f32_e32 v71, v72, v82
	v_mul_f32_e32 v71, v71, v78
	v_mul_f32_e32 v72, v73, v82
	v_mul_f32_e32 v72, v72, v79
	v_cvt_pk_bf16_f32 v71, v71, v72
	global_store_dwordx2 v[74:75], v[70:71], off offset:3072
	global_load_dwordx4 v[70:73], v[156:157], off
	v_mov_b64_e32 v[80:81], v[56:57]
	global_store_dwordx4 v144, v[66:69], s[4:5] nt
	v_mov_b64_e32 v[78:79], v[54:55]
	v_mov_b32_e32 v76, v2
	v_mul_f32_e32 v66, v66, v82
	v_mul_f32_e32 v67, v67, v82
	v_mov_b32_e32 v77, v3
	s_waitcnt vmcnt(1)
	v_mul_f32_e32 v66, v66, v70
	v_mul_f32_e32 v67, v67, v71
	v_cvt_pk_bf16_f32 v66, v66, v67
	v_mul_f32_e32 v67, v68, v82
	v_mul_f32_e32 v67, v67, v72
	v_mul_f32_e32 v68, v69, v82
	v_mul_f32_e32 v68, v68, v73
	v_cvt_pk_bf16_f32 v67, v67, v68
	global_store_dwordx2 v[74:75], v[66:67], off offset:3584
	v_mov_b64_e32 v[68:69], v[64:65]
	v_mov_b64_e32 v[72:73], v[60:61]
	v_mov_b64_e32 v[66:67], v[62:63]
	v_mov_b64_e32 v[70:71], v[58:59]
	v_mov_b32_e32 v82, v4
	v_mov_b32_e32 v74, v0
	v_mov_b32_e32 v75, v1
	s_cbranch_vccz .LBB0_1572
